# v065 + QK 1:1 read interleave + first QK reads before the LDS-DMA block
# speedup vs baseline: 1.0067x; 1.0039x over previous
.LBB0_513:
	s_waitcnt lgkmcnt(7)
	v_mfma_f32_32x32x16_bf16 v[144:159], v[192:195], v[160:163], 0
	v_add3_u32 v236, s100, v225, v220
	ds_read_b128 v[192:195], v236
	s_waitcnt lgkmcnt(7)
	v_mfma_f32_32x32x16_bf16 v[128:143], v[196:199], v[160:163], 0
	ds_read_b128 v[196:199], v236 offset:8192
	s_waitcnt lgkmcnt(7)
	v_mfma_f32_32x32x16_bf16 v[144:159], v[200:203], v[164:167], v[144:159]
	v_add3_u32 v236, s100, v227, v220
	ds_read_b128 v[200:203], v236
	s_waitcnt lgkmcnt(7)
	v_mfma_f32_32x32x16_bf16 v[128:143], v[204:207], v[164:167], v[128:143]
	ds_read_b128 v[204:207], v236 offset:8192
	s_waitcnt lgkmcnt(7)
	v_mfma_f32_32x32x16_bf16 v[144:159], v[240:243], v[168:171], v[144:159]
	v_add3_u32 v236, s100, v228, v220
	ds_read_b128 v[240:243], v236
	s_waitcnt lgkmcnt(7)
	v_mfma_f32_32x32x16_bf16 v[128:143], v[244:247], v[168:171], v[128:143]
	ds_read_b128 v[244:247], v236 offset:8192
	s_waitcnt lgkmcnt(7)
	v_mfma_f32_32x32x16_bf16 v[144:159], v[248:251], v[172:175], v[144:159]
	v_add3_u32 v236, s100, v229, v220
	ds_read_b128 v[248:251], v236
	s_waitcnt lgkmcnt(7)
	v_mfma_f32_32x32x16_bf16 v[128:143], v[252:255], v[172:175], v[128:143]
	ds_read_b128 v[252:255], v236 offset:8192
	s_waitcnt lgkmcnt(7)
	v_mfma_f32_32x32x16_bf16 v[144:159], v[192:195], v[176:179], v[144:159]
	s_waitcnt lgkmcnt(6)
	v_mfma_f32_32x32x16_bf16 v[128:143], v[196:199], v[176:179], v[128:143]
	s_waitcnt lgkmcnt(5)
	v_mfma_f32_32x32x16_bf16 v[144:159], v[200:203], v[180:183], v[144:159]
	s_waitcnt lgkmcnt(4)
	v_mfma_f32_32x32x16_bf16 v[128:143], v[204:207], v[180:183], v[128:143]
	s_waitcnt lgkmcnt(3)
	v_mfma_f32_32x32x16_bf16 v[144:159], v[240:243], v[184:187], v[144:159]
	s_waitcnt lgkmcnt(2)
	v_mfma_f32_32x32x16_bf16 v[128:143], v[244:247], v[184:187], v[128:143]
	s_waitcnt lgkmcnt(1)
	v_mfma_f32_32x32x16_bf16 v[144:159], v[248:251], v[188:191], v[144:159]
	s_waitcnt lgkmcnt(0)
	v_mfma_f32_32x32x16_bf16 v[128:143], v[252:255], v[188:191], v[128:143]
	s_nop 9
	v_max_f32_e32 v192, v144, v145
	v_max3_f32 v192, v192, v146, v147
	v_max3_f32 v192, v192, v148, v149
	v_max3_f32 v192, v192, v150, v151
	v_max3_f32 v192, v192, v152, v153
	v_max3_f32 v192, v192, v154, v155
	v_max3_f32 v192, v192, v156, v157
	v_max3_f32 v192, v192, v158, v159
	v_max3_f32 v192, v192, v128, v129
	v_max3_f32 v192, v192, v130, v131
	v_max3_f32 v192, v192, v132, v133
	v_max3_f32 v192, v192, v134, v135
	v_max3_f32 v192, v192, v136, v137
	v_max3_f32 v192, v192, v138, v139
	v_max3_f32 v192, v192, v140, v141
	v_max3_f32 v192, v192, v142, v143
	v_mov_b32_e32 v193, v192
	s_nop 1
	v_permlane32_swap_b32_e32 v192, v193
	v_max_f32_e32 v192, v192, v193
	v_sub_f32_e32 v193, v192, v231
	v_cmp_ge_f32_e32 vcc, s38, v193
	v_max_f32_e32 v234, v231, v192
	v_sub_f32_e32 v192, v231, v234
	v_mul_f32_e32 v192, 0x3e0293ee, v192
	v_exp_f32_e32 v192, v192
	s_cmp_eq_u64 vcc, exec
	s_cselect_b64 s[4:5], -1, 0
	v_cndmask_b32_e64 v233, v192, 1.0, s[4:5]
	v_cmp_gt_f32_e32 vcc, 1.0, v233
	s_cbranch_vccz .LBB0_517
	s_and_saveexec_b64 s[24:25], s[0:1]
	ds_write_b32 v226, v233 offset:128
	s_or_b64 exec, exec, s[24:25]
	s_waitcnt lgkmcnt(0)
	v_add_u32_e32 v192, s21, v210
	ds_read_b128 v[204:207], v192 offset:224
	ds_read_b128 v[200:203], v192 offset:192
	ds_read_b128 v[196:199], v192 offset:160
	ds_read_b128 v[192:195], v192 offset:128
	s_waitcnt lgkmcnt(3)
	v_pk_mul_f32 v[12:13], v[12:13], v[204:205]
	s_waitcnt lgkmcnt(2)
	v_pk_mul_f32 v[8:9], v[8:9], v[200:201]
	s_waitcnt lgkmcnt(1)
	v_pk_mul_f32 v[4:5], v[4:5], v[196:197]
	v_pk_mul_f32 v[14:15], v[14:15], v[206:207]
	v_pk_mul_f32 v[10:11], v[10:11], v[202:203]
	v_pk_mul_f32 v[6:7], v[6:7], v[198:199]
	s_waitcnt lgkmcnt(0)
	v_pk_mul_f32 v[2:3], v[2:3], v[194:195]
	v_pk_mul_f32 v[0:1], v[0:1], v[192:193]
	v_pk_mul_f32 v[124:125], v[124:125], v[204:205]
	v_pk_mul_f32 v[120:121], v[120:121], v[200:201]
	v_pk_mul_f32 v[116:117], v[116:117], v[196:197]
	v_pk_mul_f32 v[126:127], v[126:127], v[206:207]
	v_pk_mul_f32 v[122:123], v[122:123], v[202:203]
	v_pk_mul_f32 v[118:119], v[118:119], v[198:199]
	v_pk_mul_f32 v[114:115], v[114:115], v[194:195]
	v_pk_mul_f32 v[112:113], v[112:113], v[192:193]
	v_pk_mul_f32 v[108:109], v[108:109], v[204:205]
	v_pk_mul_f32 v[104:105], v[104:105], v[200:201]
	v_pk_mul_f32 v[100:101], v[100:101], v[196:197]
	v_pk_mul_f32 v[110:111], v[110:111], v[206:207]
	v_pk_mul_f32 v[106:107], v[106:107], v[202:203]
	v_pk_mul_f32 v[102:103], v[102:103], v[198:199]
	v_pk_mul_f32 v[98:99], v[98:99], v[194:195]
	v_pk_mul_f32 v[96:97], v[96:97], v[192:193]
	v_pk_mul_f32 v[92:93], v[92:93], v[204:205]
	v_pk_mul_f32 v[88:89], v[88:89], v[200:201]
	v_pk_mul_f32 v[84:85], v[84:85], v[196:197]
	v_pk_mul_f32 v[94:95], v[94:95], v[206:207]
	v_pk_mul_f32 v[90:91], v[90:91], v[202:203]
	v_pk_mul_f32 v[86:87], v[86:87], v[198:199]
	v_pk_mul_f32 v[82:83], v[82:83], v[194:195]
	v_pk_mul_f32 v[80:81], v[80:81], v[192:193]
	v_pk_mul_f32 v[76:77], v[76:77], v[204:205]
	v_pk_mul_f32 v[72:73], v[72:73], v[200:201]
	v_pk_mul_f32 v[68:69], v[68:69], v[196:197]
	v_pk_mul_f32 v[78:79], v[78:79], v[206:207]
	v_pk_mul_f32 v[74:75], v[74:75], v[202:203]
	v_pk_mul_f32 v[70:71], v[70:71], v[198:199]
	v_pk_mul_f32 v[66:67], v[66:67], v[194:195]
	v_pk_mul_f32 v[64:65], v[64:65], v[192:193]
	v_pk_mul_f32 v[60:61], v[60:61], v[204:205]
	v_pk_mul_f32 v[56:57], v[56:57], v[200:201]
	v_pk_mul_f32 v[52:53], v[52:53], v[196:197]
	v_pk_mul_f32 v[62:63], v[62:63], v[206:207]
	v_pk_mul_f32 v[58:59], v[58:59], v[202:203]
	v_pk_mul_f32 v[54:55], v[54:55], v[198:199]
	v_pk_mul_f32 v[50:51], v[50:51], v[194:195]
	v_pk_mul_f32 v[48:49], v[48:49], v[192:193]
	v_pk_mul_f32 v[44:45], v[44:45], v[204:205]
	v_pk_mul_f32 v[40:41], v[40:41], v[200:201]
	v_pk_mul_f32 v[36:37], v[36:37], v[196:197]
	v_pk_mul_f32 v[46:47], v[46:47], v[206:207]
	v_pk_mul_f32 v[42:43], v[42:43], v[202:203]
	v_pk_mul_f32 v[38:39], v[38:39], v[198:199]
	v_pk_mul_f32 v[34:35], v[34:35], v[194:195]
	v_pk_mul_f32 v[32:33], v[32:33], v[192:193]
	v_pk_mul_f32 v[28:29], v[28:29], v[204:205]
	v_pk_mul_f32 v[24:25], v[24:25], v[200:201]
	v_pk_mul_f32 v[20:21], v[20:21], v[196:197]
	v_pk_mul_f32 v[30:31], v[30:31], v[206:207]
	v_pk_mul_f32 v[26:27], v[26:27], v[202:203]
	v_pk_mul_f32 v[22:23], v[22:23], v[198:199]
	v_pk_mul_f32 v[18:19], v[18:19], v[194:195]
	v_pk_mul_f32 v[16:17], v[16:17], v[192:193]

.LBB0_906:
	s_waitcnt lgkmcnt(7)
	v_mfma_f32_32x32x16_bf16 v[144:159], v[192:195], v[160:163], 0
	v_add3_u32 v236, s100, v226, v220
	ds_read_b128 v[192:195], v236
	s_waitcnt lgkmcnt(7)
	v_mfma_f32_32x32x16_bf16 v[128:143], v[196:199], v[160:163], 0
	ds_read_b128 v[196:199], v236 offset:8192
	s_waitcnt lgkmcnt(7)
	v_mfma_f32_32x32x16_bf16 v[144:159], v[200:203], v[164:167], v[144:159]
	v_add3_u32 v236, s100, v227, v220
	ds_read_b128 v[200:203], v236
	s_waitcnt lgkmcnt(7)
	v_mfma_f32_32x32x16_bf16 v[128:143], v[204:207], v[164:167], v[128:143]
	ds_read_b128 v[204:207], v236 offset:8192
	s_waitcnt lgkmcnt(7)
	v_mfma_f32_32x32x16_bf16 v[144:159], v[240:243], v[168:171], v[144:159]
	v_add3_u32 v236, s100, v228, v220
	ds_read_b128 v[240:243], v236
	s_waitcnt lgkmcnt(7)
	v_mfma_f32_32x32x16_bf16 v[128:143], v[244:247], v[168:171], v[128:143]
	ds_read_b128 v[244:247], v236 offset:8192
	s_waitcnt lgkmcnt(7)
	v_mfma_f32_32x32x16_bf16 v[144:159], v[248:251], v[172:175], v[144:159]
	v_add3_u32 v236, s100, v229, v220
	ds_read_b128 v[248:251], v236
	s_waitcnt lgkmcnt(7)
	v_mfma_f32_32x32x16_bf16 v[128:143], v[252:255], v[172:175], v[128:143]
	ds_read_b128 v[252:255], v236 offset:8192
	s_waitcnt lgkmcnt(7)
	v_mfma_f32_32x32x16_bf16 v[144:159], v[192:195], v[176:179], v[144:159]
	s_waitcnt lgkmcnt(6)
	v_mfma_f32_32x32x16_bf16 v[128:143], v[196:199], v[176:179], v[128:143]
	s_waitcnt lgkmcnt(5)
	v_mfma_f32_32x32x16_bf16 v[144:159], v[200:203], v[180:183], v[144:159]
	s_waitcnt lgkmcnt(4)
	v_mfma_f32_32x32x16_bf16 v[128:143], v[204:207], v[180:183], v[128:143]
	s_waitcnt lgkmcnt(3)
	v_mfma_f32_32x32x16_bf16 v[144:159], v[240:243], v[184:187], v[144:159]
	s_waitcnt lgkmcnt(2)
	v_mfma_f32_32x32x16_bf16 v[128:143], v[244:247], v[184:187], v[128:143]
	s_waitcnt lgkmcnt(1)
	v_mfma_f32_32x32x16_bf16 v[144:159], v[248:251], v[188:191], v[144:159]
	s_waitcnt lgkmcnt(0)
	v_mfma_f32_32x32x16_bf16 v[128:143], v[252:255], v[188:191], v[128:143]
	v_max_f32_e32 v194, v231, v231
	s_nop 9
	v_max_f32_e32 v192, v144, v145
	v_max3_f32 v192, v192, v146, v147
	v_max3_f32 v192, v192, v148, v149
	v_max3_f32 v192, v192, v150, v151
	v_max3_f32 v192, v192, v152, v153
	v_max3_f32 v192, v192, v154, v155
	v_max3_f32 v192, v192, v156, v157
	v_max3_f32 v192, v192, v158, v159
	v_max3_f32 v192, v192, v128, v129
	v_max3_f32 v192, v192, v130, v131
	v_max3_f32 v192, v192, v132, v133
	v_max3_f32 v192, v192, v134, v135
	v_max3_f32 v192, v192, v136, v137
	v_max3_f32 v192, v192, v138, v139
	v_max3_f32 v192, v192, v140, v141
	v_max3_f32 v192, v192, v142, v143
	v_mov_b32_e32 v193, v192
	s_nop 1
	v_permlane32_swap_b32_e32 v192, v193
	v_max_f32_e32 v192, v192, v193
	v_max_f32_e32 v234, v194, v192
	v_sub_f32_e32 v193, v192, v231
	v_sub_f32_e32 v192, v231, v234
	v_mul_f32_e32 v192, 0x3e0293ee, v192
	v_exp_f32_e32 v192, v192
	v_cmp_ge_f32_e32 vcc, s42, v193
	s_cmp_eq_u64 vcc, exec
	s_cselect_b64 s[4:5], -1, 0
	v_cndmask_b32_e64 v233, v192, 1.0, s[4:5]
	v_cmp_gt_f32_e32 vcc, 1.0, v233
	s_cbranch_vccz .LBB0_910
	s_and_saveexec_b64 s[24:25], s[0:1]
	ds_write_b32 v224, v233 offset:128
	s_or_b64 exec, exec, s[24:25]
	s_waitcnt lgkmcnt(0)
	v_add_u32_e32 v192, s21, v210
	ds_read_b128 v[204:207], v192 offset:224
	ds_read_b128 v[200:203], v192 offset:192
	ds_read_b128 v[196:199], v192 offset:160
	ds_read_b128 v[192:195], v192 offset:128
	s_waitcnt lgkmcnt(3)
	v_pk_mul_f32 v[12:13], v[12:13], v[204:205]
	s_waitcnt lgkmcnt(2)
	v_pk_mul_f32 v[8:9], v[8:9], v[200:201]
	s_waitcnt lgkmcnt(1)
	v_pk_mul_f32 v[4:5], v[4:5], v[196:197]
	v_pk_mul_f32 v[14:15], v[14:15], v[206:207]
	v_pk_mul_f32 v[10:11], v[10:11], v[202:203]
	v_pk_mul_f32 v[6:7], v[6:7], v[198:199]
	s_waitcnt lgkmcnt(0)
	v_pk_mul_f32 v[2:3], v[2:3], v[194:195]
	v_pk_mul_f32 v[0:1], v[0:1], v[192:193]
	v_pk_mul_f32 v[124:125], v[124:125], v[204:205]
	v_pk_mul_f32 v[120:121], v[120:121], v[200:201]
	v_pk_mul_f32 v[116:117], v[116:117], v[196:197]
	v_pk_mul_f32 v[126:127], v[126:127], v[206:207]
	v_pk_mul_f32 v[122:123], v[122:123], v[202:203]
	v_pk_mul_f32 v[118:119], v[118:119], v[198:199]
	v_pk_mul_f32 v[114:115], v[114:115], v[194:195]
	v_pk_mul_f32 v[112:113], v[112:113], v[192:193]
	v_pk_mul_f32 v[108:109], v[108:109], v[204:205]
	v_pk_mul_f32 v[104:105], v[104:105], v[200:201]
	v_pk_mul_f32 v[100:101], v[100:101], v[196:197]
	v_pk_mul_f32 v[110:111], v[110:111], v[206:207]
	v_pk_mul_f32 v[106:107], v[106:107], v[202:203]
	v_pk_mul_f32 v[102:103], v[102:103], v[198:199]
	v_pk_mul_f32 v[98:99], v[98:99], v[194:195]
	v_pk_mul_f32 v[96:97], v[96:97], v[192:193]
	v_pk_mul_f32 v[92:93], v[92:93], v[204:205]
	v_pk_mul_f32 v[88:89], v[88:89], v[200:201]
	v_pk_mul_f32 v[84:85], v[84:85], v[196:197]
	v_pk_mul_f32 v[94:95], v[94:95], v[206:207]
	v_pk_mul_f32 v[90:91], v[90:91], v[202:203]
	v_pk_mul_f32 v[86:87], v[86:87], v[198:199]
	v_pk_mul_f32 v[82:83], v[82:83], v[194:195]
	v_pk_mul_f32 v[80:81], v[80:81], v[192:193]
	v_pk_mul_f32 v[76:77], v[76:77], v[204:205]
	v_pk_mul_f32 v[72:73], v[72:73], v[200:201]
	v_pk_mul_f32 v[68:69], v[68:69], v[196:197]
	v_pk_mul_f32 v[78:79], v[78:79], v[206:207]
	v_pk_mul_f32 v[74:75], v[74:75], v[202:203]
	v_pk_mul_f32 v[70:71], v[70:71], v[198:199]
	v_pk_mul_f32 v[66:67], v[66:67], v[194:195]
	v_pk_mul_f32 v[64:65], v[64:65], v[192:193]
	v_pk_mul_f32 v[60:61], v[60:61], v[204:205]
	v_pk_mul_f32 v[56:57], v[56:57], v[200:201]
	v_pk_mul_f32 v[52:53], v[52:53], v[196:197]
	v_pk_mul_f32 v[62:63], v[62:63], v[206:207]
	v_pk_mul_f32 v[58:59], v[58:59], v[202:203]
	v_pk_mul_f32 v[54:55], v[54:55], v[198:199]
	v_pk_mul_f32 v[50:51], v[50:51], v[194:195]
	v_pk_mul_f32 v[48:49], v[48:49], v[192:193]
	v_pk_mul_f32 v[44:45], v[44:45], v[204:205]
	v_pk_mul_f32 v[40:41], v[40:41], v[200:201]
	v_pk_mul_f32 v[36:37], v[36:37], v[196:197]
	v_pk_mul_f32 v[46:47], v[46:47], v[206:207]
	v_pk_mul_f32 v[42:43], v[42:43], v[202:203]
	v_pk_mul_f32 v[38:39], v[38:39], v[198:199]
	v_pk_mul_f32 v[34:35], v[34:35], v[194:195]
	v_pk_mul_f32 v[32:33], v[32:33], v[192:193]
	v_pk_mul_f32 v[28:29], v[28:29], v[204:205]
	v_pk_mul_f32 v[24:25], v[24:25], v[200:201]
	v_pk_mul_f32 v[20:21], v[20:21], v[196:197]
	v_pk_mul_f32 v[30:31], v[30:31], v[206:207]
	v_pk_mul_f32 v[26:27], v[26:27], v[202:203]
	v_pk_mul_f32 v[22:23], v[22:23], v[198:199]
	v_pk_mul_f32 v[18:19], v[18:19], v[194:195]
	v_pk_mul_f32 v[16:17], v[16:17], v[192:193]
